# attention: K-tile LDS writes moved ahead of the first per-tile barrier (only the V write stays between the two barriers)
# speedup vs baseline: 1.0023x; 1.0023x over previous
.LBB0_716:
	s_waitcnt vmcnt(3)
	ds_write_b128 v173, v[124:127] offset:16384
	ds_write_b128 v174, v[128:131] offset:16384
	s_barrier
	v_cmp_gt_f32_e32 vcc, 1.0, v181
	ds_write_b128 v176, v[120:123]
	s_cbranch_vccz .LBB0_720
	s_and_saveexec_b64 s[2:3], s[40:41]
	ds_write_b32 v164, v181 offset:49280
	s_or_b64 exec, exec, s[2:3]
	s_waitcnt lgkmcnt(0)
	v_add_u32_e32 v60, v163, v188
	ds_read_b128 v[48:51], v60 offset:49376
	ds_read_b128 v[52:55], v60 offset:49344
	ds_read_b128 v[56:59], v60 offset:49312
	ds_read_b128 v[60:63], v60 offset:49280
	s_waitcnt lgkmcnt(3)
	v_pk_mul_f32 v[28:29], v[28:29], v[48:49]
	s_waitcnt lgkmcnt(2)
	v_pk_mul_f32 v[24:25], v[24:25], v[52:53]
	s_waitcnt lgkmcnt(1)
	v_pk_mul_f32 v[20:21], v[20:21], v[56:57]
	v_pk_mul_f32 v[30:31], v[30:31], v[50:51]
	v_pk_mul_f32 v[26:27], v[26:27], v[54:55]
	v_pk_mul_f32 v[22:23], v[22:23], v[58:59]
	s_waitcnt lgkmcnt(0)
	v_pk_mul_f32 v[18:19], v[18:19], v[62:63]
	v_pk_mul_f32 v[16:17], v[16:17], v[60:61]
	v_pk_mul_f32 v[12:13], v[12:13], v[48:49]
	v_pk_mul_f32 v[8:9], v[8:9], v[52:53]
	v_pk_mul_f32 v[4:5], v[4:5], v[56:57]
	v_pk_mul_f32 v[14:15], v[14:15], v[50:51]
	v_pk_mul_f32 v[10:11], v[10:11], v[54:55]
	v_pk_mul_f32 v[6:7], v[6:7], v[58:59]
	v_pk_mul_f32 v[2:3], v[2:3], v[62:63]
	v_pk_mul_f32 v[0:1], v[0:1], v[60:61]

.LBB0_721:
	s_waitcnt vmcnt(3)
	ds_write_b128 v173, v[136:139] offset:32768
	ds_write_b128 v174, v[140:143] offset:32768
	s_barrier
	v_cmp_gt_f32_e32 vcc, 1.0, v66
	ds_write_b128 v176, v[132:135] offset:8192
	s_cbranch_vccz .LBB0_725
	s_and_saveexec_b64 s[2:3], s[40:41]
	ds_write_b32 v164, v66 offset:49280
	s_or_b64 exec, exec, s[2:3]
	s_waitcnt lgkmcnt(0)
	v_add_u32_e32 v67, v163, v188
	ds_read_b128 v[68:71], v67 offset:49376
	ds_read_b128 v[72:75], v67 offset:49344
	ds_read_b128 v[76:79], v67 offset:49312
	ds_read_b128 v[132:135], v67 offset:49280
	s_waitcnt lgkmcnt(3)
	v_pk_mul_f32 v[28:29], v[28:29], v[68:69]
	s_waitcnt lgkmcnt(2)
	v_pk_mul_f32 v[24:25], v[24:25], v[72:73]
	s_waitcnt lgkmcnt(1)
	v_pk_mul_f32 v[20:21], v[20:21], v[76:77]
	v_pk_mul_f32 v[30:31], v[30:31], v[70:71]
	v_pk_mul_f32 v[26:27], v[26:27], v[74:75]
	v_pk_mul_f32 v[22:23], v[22:23], v[78:79]
	s_waitcnt lgkmcnt(0)
	v_pk_mul_f32 v[18:19], v[18:19], v[134:135]
	v_pk_mul_f32 v[16:17], v[16:17], v[132:133]
	v_pk_mul_f32 v[12:13], v[12:13], v[68:69]
	v_pk_mul_f32 v[8:9], v[8:9], v[72:73]
	v_pk_mul_f32 v[4:5], v[4:5], v[76:77]
	v_pk_mul_f32 v[14:15], v[14:15], v[70:71]
	v_pk_mul_f32 v[10:11], v[10:11], v[74:75]
	v_pk_mul_f32 v[6:7], v[6:7], v[78:79]
	v_pk_mul_f32 v[2:3], v[2:3], v[134:135]
	v_pk_mul_f32 v[0:1], v[0:1], v[132:133]

.LBB0_734:
	s_waitcnt vmcnt(3)
	ds_write_b128 v173, v[124:127] offset:16384
	ds_write_b128 v174, v[128:131] offset:16384
	s_barrier
	v_cmp_gt_f32_e32 vcc, 1.0, v186
	ds_write_b128 v176, v[120:123]
	s_cbranch_vccz .LBB0_738
	s_and_saveexec_b64 s[0:1], s[40:41]
	ds_write_b32 v164, v186 offset:49280
	s_or_b64 exec, exec, s[0:1]
	s_waitcnt lgkmcnt(0)
	v_add_u32_e32 v60, v163, v188
	ds_read_b128 v[48:51], v60 offset:49376
	ds_read_b128 v[52:55], v60 offset:49344
	ds_read_b128 v[56:59], v60 offset:49312
	ds_read_b128 v[60:63], v60 offset:49280
	s_waitcnt lgkmcnt(3)
	v_pk_mul_f32 v[28:29], v[28:29], v[48:49]
	s_waitcnt lgkmcnt(2)
	v_pk_mul_f32 v[24:25], v[24:25], v[52:53]
	s_waitcnt lgkmcnt(1)
	v_pk_mul_f32 v[20:21], v[20:21], v[56:57]
	v_pk_mul_f32 v[30:31], v[30:31], v[50:51]
	v_pk_mul_f32 v[26:27], v[26:27], v[54:55]
	v_pk_mul_f32 v[22:23], v[22:23], v[58:59]
	s_waitcnt lgkmcnt(0)
	v_pk_mul_f32 v[18:19], v[18:19], v[62:63]
	v_pk_mul_f32 v[16:17], v[16:17], v[60:61]
	v_pk_mul_f32 v[12:13], v[12:13], v[48:49]
	v_pk_mul_f32 v[8:9], v[8:9], v[52:53]
	v_pk_mul_f32 v[4:5], v[4:5], v[56:57]
	v_pk_mul_f32 v[14:15], v[14:15], v[50:51]
	v_pk_mul_f32 v[10:11], v[10:11], v[54:55]
	v_pk_mul_f32 v[6:7], v[6:7], v[58:59]
	v_pk_mul_f32 v[2:3], v[2:3], v[62:63]
	v_pk_mul_f32 v[0:1], v[0:1], v[60:61]

.LBB0_739:
	s_waitcnt vmcnt(3)
	ds_write_b128 v173, v[136:139] offset:32768
	ds_write_b128 v174, v[140:143] offset:32768
	s_barrier
	v_cmp_gt_f32_e32 vcc, 1.0, v181
	ds_write_b128 v176, v[132:135] offset:8192
	s_cbranch_vccz .LBB0_743
	s_and_saveexec_b64 s[0:1], s[40:41]
	ds_write_b32 v164, v181 offset:49280
	s_or_b64 exec, exec, s[0:1]
	s_waitcnt lgkmcnt(0)
	v_add_u32_e32 v78, v163, v188
	ds_read_b128 v[66:69], v78 offset:49376
	ds_read_b128 v[70:73], v78 offset:49344
	ds_read_b128 v[74:77], v78 offset:49312
	ds_read_b128 v[132:135], v78 offset:49280
	s_waitcnt lgkmcnt(3)
	v_pk_mul_f32 v[28:29], v[28:29], v[66:67]
	s_waitcnt lgkmcnt(2)
	v_pk_mul_f32 v[24:25], v[24:25], v[70:71]
	s_waitcnt lgkmcnt(1)
	v_pk_mul_f32 v[20:21], v[20:21], v[74:75]
	v_pk_mul_f32 v[30:31], v[30:31], v[68:69]
	v_pk_mul_f32 v[26:27], v[26:27], v[72:73]
	v_pk_mul_f32 v[22:23], v[22:23], v[76:77]
	s_waitcnt lgkmcnt(0)
	v_pk_mul_f32 v[18:19], v[18:19], v[134:135]
	v_pk_mul_f32 v[16:17], v[16:17], v[132:133]
	v_pk_mul_f32 v[12:13], v[12:13], v[66:67]
	v_pk_mul_f32 v[8:9], v[8:9], v[70:71]
	v_pk_mul_f32 v[4:5], v[4:5], v[74:75]
	v_pk_mul_f32 v[14:15], v[14:15], v[68:69]
	v_pk_mul_f32 v[10:11], v[10:11], v[72:73]
	v_pk_mul_f32 v[6:7], v[6:7], v[76:77]
	v_pk_mul_f32 v[2:3], v[2:3], v[134:135]
	v_pk_mul_f32 v[0:1], v[0:1], v[132:133]
